# NSA selected blocks (non-diagonal): 16 per-element limit compares+selects replaced by one per-lane 0/-inf bias folded into the scaling fma (on top of window fast path)
# baseline (speedup 1.0000x reference)
; #define SB0 __builtin_amdgcn_sched_barrier(0)
; __device__ __forceinline__ void qk64_lim(const bf16x8 (&kq)[8], const bf16x8 (&qf)[2], float scale, int lim2,
;                                          f32x4 (&st)[4]) {
; #pragma unroll
;   for (int kt = 0; kt < 4; ++kt) {
;     f32x4 z = {0.f, 0.f, 0.f, 0.f};
;     z = mfma16(kq[2 * kt], qf[0], z);
;     z = mfma16(kq[2 * kt + 1], qf[1], z);
; #pragma unroll
;     for (int r = 0; r < 4; ++r) st[kt][r] = ((kt * 16 + r) <= lim2) ? z[r] * scale : -INFINITY;
;   }
; }
; __device__ __forceinline__ void phase_nsa_attn(const Params& p, char* smem, volatile LAS unsigned* vb_) {
;     ...
;       for (int i = 0; i < ntot; ++i) {
;         const int j = jn;
;         if (i + 1 < ntot) advance();
;         const bool mine = (((j < 64) ? (my0 >> j) : (my1 >> (j - 64))) & 1ull) != 0ull;
;         const int lim2 = (mine ? ((j == cur) ? (s - j * 64) : 63) : -1) - q * 4;
;         f32x4 st[4];
;         qk64_lim(kA, qf, scale, lim2, st);
;         SB0;
;         k_load64(kA, Ks + (size_t)jn * 4096, lane);
;         SB0;
;         softmax_update(st, m, lsum, o);
;         pv64(vA, st, o);
;         SB0;
;         v_load64(vA, Vs + (size_t)jn * 4096, lane);
;         SB0;
.LBB0_178:
	s_cmp_lt_i32 s36, 64
	s_waitcnt vmcnt(15)
	v_mfma_f32_16x16x32_bf16 v[88:91], v[88:91], v[4:7], 0
	s_cselect_b64 vcc, -1, 0
	s_sub_i32 s0, s36, 64
	v_lshrrev_b64 v[2:3], s36, v[92:93]
	v_lshrrev_b64 v[98:99], s0, v[94:95]
	s_cmp_eq_u32 s36, s60
	v_cndmask_b32_e32 v0, v98, v2, vcc
	s_cselect_b64 vcc, -1, 0
	s_lshl_b32 s0, s36, 6
	v_subrev_u32_e32 v2, s0, v155
	v_and_b32_e32 v0, 1, v0
	s_waitcnt vmcnt(14)
	v_mfma_f32_16x16x32_bf16 v[84:87], v[84:87], v[8:11], v[88:91]
	v_cndmask_b32_e32 v2, 63, v2, vcc
	v_cmp_eq_u32_e32 vcc, 1, v0
	s_waitcnt vmcnt(13)
	v_mfma_f32_16x16x32_bf16 v[80:83], v[80:83], v[4:7], 0
	v_cndmask_b32_e32 v0, -1, v2, vcc
	v_sub_u32_e32 v0, v0, v150
	s_cmp_lg_u32 s36, s60
	s_cbranch_scc1 .Lsel_semi
	s_nop 1
	v_mul_f32_e32 v2, 0x3e38aa3b, v84
	v_cmp_lt_i32_e32 vcc, -1, v0
	s_waitcnt vmcnt(12)
	v_mfma_f32_16x16x32_bf16 v[76:79], v[76:79], v[8:11], v[80:83]
	v_cndmask_b32_e32 v101, v203, v2, vcc
	v_mul_f32_e32 v2, 0x3e38aa3b, v85
	s_waitcnt vmcnt(11)
	v_mfma_f32_16x16x32_bf16 v[60:63], v[60:63], v[4:7], 0
	v_cmp_lt_i32_e32 vcc, 0, v0
	s_nop 1
	v_cndmask_b32_e32 v99, v203, v2, vcc
	v_mul_f32_e32 v2, 0x3e38aa3b, v86
	v_cmp_lt_i32_e32 vcc, 1, v0
	s_waitcnt vmcnt(10)
	v_mfma_f32_16x16x32_bf16 v[52:55], v[52:55], v[8:11], v[60:63]
	v_cndmask_b32_e32 v98, v203, v2, vcc
	v_mul_f32_e32 v2, 0x3e38aa3b, v87
	v_cmp_lt_i32_e32 vcc, 2, v0
	s_waitcnt vmcnt(9)
	v_mfma_f32_16x16x32_bf16 v[44:47], v[44:47], v[4:7], 0
	v_cndmask_b32_e32 v3, v203, v2, vcc
	v_mul_f32_e32 v2, 0x3e38aa3b, v76
	v_cmp_lt_i32_e32 vcc, 15, v0
	s_waitcnt vmcnt(8)
	v_mfma_f32_16x16x32_bf16 v[28:31], v[28:31], v[8:11], v[44:47]
	v_cndmask_b32_e32 v105, v203, v2, vcc
	v_mul_f32_e32 v2, 0x3e38aa3b, v77
	v_cmp_lt_i32_e32 vcc, 16, v0
	s_nop 1
	v_cndmask_b32_e32 v103, v203, v2, vcc
	v_mul_f32_e32 v2, 0x3e38aa3b, v78
	v_cmp_lt_i32_e32 vcc, 17, v0
	s_nop 1
	v_cndmask_b32_e32 v102, v203, v2, vcc
	v_mul_f32_e32 v2, 0x3e38aa3b, v79
	v_cmp_lt_i32_e32 vcc, 18, v0
	s_nop 1
	v_cndmask_b32_e32 v100, v203, v2, vcc
	v_mul_f32_e32 v2, 0x3e38aa3b, v52
	v_cmp_lt_i32_e32 vcc, 31, v0
	s_nop 1
	v_cndmask_b32_e32 v108, v203, v2, vcc
	v_mul_f32_e32 v2, 0x3e38aa3b, v53
	v_cmp_lt_i32_e32 vcc, 32, v0
	s_nop 1
	v_cndmask_b32_e32 v107, v203, v2, vcc
	v_mul_f32_e32 v2, 0x3e38aa3b, v54
	v_cmp_lt_i32_e32 vcc, 33, v0
	s_nop 1
	v_cndmask_b32_e32 v106, v203, v2, vcc
	v_mul_f32_e32 v2, 0x3e38aa3b, v55
	v_cmp_lt_i32_e32 vcc, 34, v0
	s_nop 1
	v_cndmask_b32_e32 v104, v203, v2, vcc
	v_mul_f32_e32 v2, 0x3e38aa3b, v28
	v_cmp_lt_i32_e32 vcc, 47, v0
	s_nop 1
	v_cndmask_b32_e32 v109, v203, v2, vcc
	v_mul_f32_e32 v2, 0x3e38aa3b, v29
	v_cmp_lt_i32_e32 vcc, 48, v0
	s_nop 1
	v_cndmask_b32_e32 v110, v203, v2, vcc
	v_mul_f32_e32 v2, 0x3e38aa3b, v30
	v_cmp_lt_i32_e32 vcc, 49, v0
	s_nop 1
	v_cndmask_b32_e32 v111, v203, v2, vcc
	v_mul_f32_e32 v2, 0x3e38aa3b, v31
	v_cmp_lt_i32_e32 vcc, 50, v0
	s_nop 1
	v_cndmask_b32_e32 v112, v203, v2, vcc
	s_lshl_b64 s[0:1], s[58:59], 13
	v_lshl_add_u64 v[28:29], v[146:147], 0, s[0:1]
	global_load_dwordx4 v[88:91], v[28:29], off
	global_load_dwordx4 v[84:87], v[28:29], off offset:1024
	global_load_dwordx4 v[80:83], v[28:29], off offset:2048
	global_load_dwordx4 v[76:79], v[28:29], off offset:3072
	v_add_co_u32_e32 v28, vcc, s33, v28
	s_nop 1
	v_addc_co_u32_e32 v29, vcc, 0, v29, vcc
	global_load_dwordx4 v[60:63], v[28:29], off
	global_load_dwordx4 v[52:55], v[28:29], off offset:1024
	global_load_dwordx4 v[44:47], v[28:29], off offset:2048
	s_nop 0
	global_load_dwordx4 v[28:31], v[28:29], off offset:3072
	v_max3_f32 v0, v101, s3, v99
	v_max3_f32 v0, v0, v98, v3
	v_max3_f32 v0, v0, v105, v103
	v_max3_f32 v0, v0, v102, v100
	v_max3_f32 v0, v0, v108, v107
	v_max3_f32 v0, v0, v106, v104
	v_max3_f32 v0, v0, v109, v110
	v_max3_f32 v0, v0, v111, v112
	v_mov_b32_e32 v2, v0
	s_nop 1
	v_permlane16_swap_b32_e32 v2, v0
	v_max_f32_e32 v0, v0, v2
	v_mov_b32_e32 v2, v0
	s_nop 1
	v_permlane32_swap_b32_e32 v2, v0
	v_max3_f32 v2, v97, v0, v2
	v_sub_f32_e32 v0, v97, v2
	v_exp_f32_e32 v0, v0
	s_nop 0
	v_cmp_neq_f32_e32 vcc, 1.0, v0
	s_cbranch_vccz .LBB0_180
	v_pk_mul_f32 v[26:27], v[26:27], v[0:1] op_sel_hi:[1,0]
	v_pk_mul_f32 v[24:25], v[24:25], v[0:1] op_sel_hi:[1,0]
	v_pk_mul_f32 v[22:23], v[22:23], v[0:1] op_sel_hi:[1,0]
	v_pk_mul_f32 v[20:21], v[20:21], v[0:1] op_sel_hi:[1,0]
	v_pk_mul_f32 v[18:19], v[18:19], v[0:1] op_sel_hi:[1,0]
	v_pk_mul_f32 v[16:17], v[16:17], v[0:1] op_sel_hi:[1,0]
	v_pk_mul_f32 v[14:15], v[14:15], v[0:1] op_sel_hi:[1,0]
	v_pk_mul_f32 v[12:13], v[12:13], v[0:1] op_sel_hi:[1,0]

; #define EXP2F(x) __builtin_amdgcn_exp2f(x)
; #define SB0 __builtin_amdgcn_sched_barrier(0)
; __device__ __forceinline__ void softmax_update(f32x4 (&st)[4], float& m, float& lsum, f32x4 (&o)[4]) {
;   float mx = -1e30f;
; #pragma unroll
;   for (int kt = 0; kt < 4; ++kt)
; #pragma unroll
;     for (int r = 0; r < 4; ++r) mx = fmaxf(mx, st[kt][r]);
;   mx = fmaxf(mx, __shfl_xor(mx, 16));
;   mx = fmaxf(mx, __shfl_xor(mx, 32));
;   const float mnew = fmaxf(m, mx);
;   const float alpha = EXP2F(m - mnew);
;   float ps = 0.f;
; #pragma unroll
;   for (int kt = 0; kt < 4; ++kt)
; #pragma unroll
;     for (int r = 0; r < 4; ++r) {
;       const float pv = EXP2F(st[kt][r] - mnew);
;       st[kt][r] = pv;
;       ps += pv;
;     }
;   lsum = lsum * alpha + ps;
;   m = mnew;
;   if (__builtin_amdgcn_ballot_w64(alpha != 1.0f)) {
; #pragma unroll
;     for (int dt = 0; dt < 4; ++dt) o[dt] *= alpha;
;   }
; __device__ __forceinline__ void phase_nsa_attn(const Params& p, char* smem, volatile LAS unsigned* vb_) {
;     ...
;         qk64_lim(kA, qf, scale, lim2, st);
;         SB0;
;         k_load64(kA, Ks + (size_t)jn * 4096, lane);
;         SB0;
;         softmax_update(st, m, lsum, o);
;         pv64(vA, st, o);
;         SB0;
;         v_load64(vA, Vs + (size_t)jn * 4096, lane);
;         SB0;
.Lsel_semi:
	v_cndmask_b32_e32 v0, v203, v1, vcc
	s_mov_b32 s98, 0x3e38aa3b
	s_waitcnt vmcnt(12)
	v_mfma_f32_16x16x32_bf16 v[76:79], v[76:79], v[8:11], v[80:83]
	s_waitcnt vmcnt(11)
	v_mfma_f32_16x16x32_bf16 v[60:63], v[60:63], v[4:7], 0
	s_waitcnt vmcnt(10)
	v_mfma_f32_16x16x32_bf16 v[52:55], v[52:55], v[8:11], v[60:63]
	s_waitcnt vmcnt(9)
	v_mfma_f32_16x16x32_bf16 v[44:47], v[44:47], v[4:7], 0
	s_waitcnt vmcnt(8)
	v_mfma_f32_16x16x32_bf16 v[28:31], v[28:31], v[8:11], v[44:47]
	v_fma_f32 v101, v84, s98, v0
	v_fma_f32 v99, v85, s98, v0
	v_fma_f32 v98, v86, s98, v0
	v_fma_f32 v3, v87, s98, v0
	v_fma_f32 v105, v76, s98, v0
	v_fma_f32 v103, v77, s98, v0
	v_fma_f32 v102, v78, s98, v0
	v_fma_f32 v100, v79, s98, v0
	v_fma_f32 v108, v52, s98, v0
	v_fma_f32 v107, v53, s98, v0
	v_fma_f32 v106, v54, s98, v0
	v_fma_f32 v104, v55, s98, v0
	v_fma_f32 v109, v28, s98, v0
	v_fma_f32 v110, v29, s98, v0
	v_fma_f32 v111, v30, s98, v0
	v_fma_f32 v112, v31, s98, v0
	s_lshl_b64 s[0:1], s[58:59], 13
	v_lshl_add_u64 v[28:29], v[146:147], 0, s[0:1]
	global_load_dwordx4 v[88:91], v[28:29], off
	global_load_dwordx4 v[84:87], v[28:29], off offset:1024
	global_load_dwordx4 v[80:83], v[28:29], off offset:2048
	global_load_dwordx4 v[76:79], v[28:29], off offset:3072
	v_add_co_u32_e32 v28, vcc, s33, v28
	s_nop 1
	v_addc_co_u32_e32 v29, vcc, 0, v29, vcc
	global_load_dwordx4 v[60:63], v[28:29], off
	global_load_dwordx4 v[52:55], v[28:29], off offset:1024
	global_load_dwordx4 v[44:47], v[28:29], off offset:2048
	s_nop 0
	global_load_dwordx4 v[28:31], v[28:29], off offset:3072
	v_max3_f32 v0, v101, s3, v99
	v_max3_f32 v0, v0, v98, v3
	v_max3_f32 v0, v0, v105, v103
	v_max3_f32 v0, v0, v102, v100
	v_max3_f32 v0, v0, v108, v107
	v_max3_f32 v0, v0, v106, v104
	v_max3_f32 v0, v0, v109, v110
	v_max3_f32 v0, v0, v111, v112
	v_mov_b32_e32 v2, v0
	s_nop 1
	v_permlane16_swap_b32_e32 v2, v0
	v_max_f32_e32 v0, v0, v2
	v_mov_b32_e32 v2, v0
	s_nop 1
	v_permlane32_swap_b32_e32 v2, v0
	v_max3_f32 v2, v97, v0, v2
	v_sub_f32_e32 v0, v97, v2
	v_exp_f32_e32 v0, v0
	s_nop 0
	v_cmp_neq_f32_e32 vcc, 1.0, v0
	s_cbranch_vccz .LBB0_180
	v_pk_mul_f32 v[26:27], v[26:27], v[0:1] op_sel_hi:[1,0]
	v_pk_mul_f32 v[24:25], v[24:25], v[0:1] op_sel_hi:[1,0]
	v_pk_mul_f32 v[22:23], v[22:23], v[0:1] op_sel_hi:[1,0]
	v_pk_mul_f32 v[20:21], v[20:21], v[0:1] op_sel_hi:[1,0]
	v_pk_mul_f32 v[18:19], v[18:19], v[0:1] op_sel_hi:[1,0]
	v_pk_mul_f32 v[16:17], v[16:17], v[0:1] op_sel_hi:[1,0]
	v_pk_mul_f32 v[14:15], v[14:15], v[0:1] op_sel_hi:[1,0]
	v_pk_mul_f32 v[12:13], v[12:13], v[0:1] op_sel_hi:[1,0]
	s_branch .LBB0_180
